# attention mask-free softmax row sums via v_pk_add_f32 trees (9 instead of 17 VALU per half) on top of v086
# baseline (speedup 1.0000x reference)
.Lnd_107:
	s_and_b32 s33, s42, 1
	s_mul_i32 s6, s33, 0x9000
	v_add_u32_e32 v199, s6, v187
	v_add_u32_e32 v198, s6, v188
	s_mov_b64 s[54:55], exec
	v_readfirstlane_b32 s4, v186
	s_bitcmp1_b32 s4, 8
	s_cbranch_scc1 .Lab_B
	ds_read_b128 v[202:205], v199
	ds_read_b128 v[206:209], v199 offset:32
	ds_read_b128 v[210:213], v193
	ds_read_b128 v[214:217], v193 offset:32
	ds_read_b128 v[218:221], v199 offset:64
	ds_read_b128 v[222:225], v199 offset:96
	ds_read_b128 v[226:229], v193 offset:64
	ds_read_b128 v[230:233], v193 offset:96
	s_waitcnt lgkmcnt(5)
	v_mfma_f32_32x32x16_bf16 v[144:159], v[202:205], v[210:213], v[0:15]
	s_waitcnt lgkmcnt(4)
	v_mfma_f32_32x32x16_bf16 v[144:159], v[206:209], v[214:217], v[144:159]
	s_waitcnt lgkmcnt(1)
	v_mfma_f32_32x32x16_bf16 v[144:159], v[218:221], v[226:229], v[144:159]
	s_waitcnt lgkmcnt(0)
	v_mfma_f32_32x32x16_bf16 v[144:159], v[222:225], v[230:233], v[144:159]
	s_nop 11
	v_exp_f32_e32 v146, v146
	v_exp_f32_e32 v147, v147
	v_exp_f32_e32 v148, v148
	v_exp_f32_e32 v149, v149
	v_exp_f32_e32 v150, v150
	v_exp_f32_e32 v151, v151
	v_exp_f32_e32 v152, v152
	v_exp_f32_e32 v153, v153
	v_exp_f32_e32 v144, v144
	v_exp_f32_e32 v154, v154
	v_exp_f32_e32 v145, v145
	v_exp_f32_e32 v155, v155
	v_exp_f32_e32 v156, v156
	v_exp_f32_e32 v157, v157
	v_exp_f32_e32 v158, v158
	v_exp_f32_e32 v159, v159
	v_pk_add_f32 v[244:245], v[144:145], v[146:147]
	v_pk_add_f32 v[246:247], v[148:149], v[150:151]
	v_pk_add_f32 v[244:245], v[244:245], v[152:153]
	v_pk_add_f32 v[246:247], v[246:247], v[154:155]
	v_pk_add_f32 v[244:245], v[244:245], v[156:157]
	v_pk_add_f32 v[246:247], v[246:247], v[158:159]
	v_pk_add_f32 v[244:245], v[244:245], v[246:247]
	v_add_f32_e32 v244, v244, v245
	v_add_f32_e32 v196, v196, v244
	v_cvt_pk_bf16_f32 v202, v144, v145
	v_cvt_pk_bf16_f32 v203, v146, v147
	v_cvt_pk_bf16_f32 v204, v148, v149
	v_cvt_pk_bf16_f32 v205, v150, v151
	v_cvt_pk_bf16_f32 v206, v152, v153
	v_cvt_pk_bf16_f32 v207, v154, v155
	v_cvt_pk_bf16_f32 v208, v156, v157
	v_cvt_pk_bf16_f32 v209, v158, v159
	ds_read_b128 v[210:213], v199 offset:9216
	ds_read_b128 v[214:217], v199 offset:9248
	ds_read_b128 v[218:221], v193 offset:36864
	ds_read_b128 v[222:225], v193 offset:36896
	ds_read_b128 v[226:229], v199 offset:9280
	ds_read_b128 v[230:233], v199 offset:9312
	ds_read_b128 v[234:237], v193 offset:36928
	ds_read_b128 v[238:241], v193 offset:36960
	s_waitcnt lgkmcnt(5)
	v_mfma_f32_32x32x16_bf16 v[144:159], v[210:213], v[218:221], v[0:15]
	s_waitcnt lgkmcnt(4)
	v_mfma_f32_32x32x16_bf16 v[144:159], v[214:217], v[222:225], v[144:159]
	ds_read_b128 v[210:213], v198
	ds_read_b128 v[214:217], v198 offset:32
	ds_read_b128 v[218:221], v198 offset:4608
	ds_read_b128 v[222:225], v198 offset:4640
	s_waitcnt lgkmcnt(5)
	v_mfma_f32_32x32x16_bf16 v[144:159], v[226:229], v[234:237], v[144:159]
	s_waitcnt lgkmcnt(4)
	v_mfma_f32_32x32x16_bf16 v[144:159], v[230:233], v[238:241], v[144:159]
	s_nop 11
	v_exp_f32_e32 v144, v144
	v_exp_f32_e32 v145, v145
	v_exp_f32_e32 v146, v146
	v_exp_f32_e32 v147, v147
	v_exp_f32_e32 v148, v148
	v_exp_f32_e32 v149, v149
	v_exp_f32_e32 v150, v150
	v_exp_f32_e32 v151, v151
	v_exp_f32_e32 v152, v152
	v_exp_f32_e32 v153, v153
	v_exp_f32_e32 v154, v154
	v_exp_f32_e32 v155, v155
	v_exp_f32_e32 v156, v156
	v_exp_f32_e32 v157, v157
	v_exp_f32_e32 v158, v158
	v_exp_f32_e32 v159, v159
	v_pk_add_f32 v[244:245], v[144:145], v[146:147]
	v_pk_add_f32 v[246:247], v[148:149], v[150:151]
	v_pk_add_f32 v[244:245], v[244:245], v[152:153]
	v_pk_add_f32 v[246:247], v[246:247], v[154:155]
	v_pk_add_f32 v[244:245], v[244:245], v[156:157]
	v_pk_add_f32 v[246:247], v[246:247], v[158:159]
	v_pk_add_f32 v[244:245], v[244:245], v[246:247]
	v_add_f32_e32 v244, v244, v245
	v_add_f32_e32 v197, v197, v244
	v_cvt_pk_bf16_f32 v144, v144, v145
	v_cvt_pk_bf16_f32 v145, v146, v147
	v_cvt_pk_bf16_f32 v146, v148, v149
	v_cvt_pk_bf16_f32 v147, v150, v151
	v_cvt_pk_bf16_f32 v148, v152, v153
	v_cvt_pk_bf16_f32 v149, v154, v155
	v_cvt_pk_bf16_f32 v150, v156, v157
	v_cvt_pk_bf16_f32 v151, v158, v159
	ds_read_b128 v[152:155], v198 offset:9216
	ds_read_b128 v[156:159], v198 offset:9248
	ds_read_b128 v[226:229], v198 offset:13824
	ds_read_b128 v[230:233], v198 offset:13856
	s_waitcnt lgkmcnt(7)
	v_mfma_f32_32x32x16_bf16 v[112:127], v[210:213], v[202:205], v[112:127]
	v_mfma_f32_32x32x16_bf16 v[128:143], v[210:213], v[144:147], v[128:143]
	s_waitcnt lgkmcnt(5)
	v_mfma_f32_32x32x16_bf16 v[80:95], v[218:221], v[202:205], v[80:95]
	v_mfma_f32_32x32x16_bf16 v[96:111], v[218:221], v[144:147], v[96:111]
	v_mfma_f32_32x32x16_bf16 v[112:127], v[214:217], v[206:209], v[112:127]
	v_mfma_f32_32x32x16_bf16 v[128:143], v[214:217], v[148:151], v[128:143]
	s_waitcnt lgkmcnt(4)
	v_mfma_f32_32x32x16_bf16 v[80:95], v[222:225], v[206:209], v[80:95]
	v_mfma_f32_32x32x16_bf16 v[96:111], v[222:225], v[148:151], v[96:111]
	s_waitcnt lgkmcnt(3)
	v_mfma_f32_32x32x16_bf16 v[48:63], v[152:155], v[202:205], v[48:63]
	v_mfma_f32_32x32x16_bf16 v[64:79], v[152:155], v[144:147], v[64:79]
	s_waitcnt lgkmcnt(1)
	v_mfma_f32_32x32x16_bf16 v[16:31], v[226:229], v[202:205], v[16:31]
	v_mfma_f32_32x32x16_bf16 v[32:47], v[226:229], v[144:147], v[32:47]
	v_mfma_f32_32x32x16_bf16 v[48:63], v[156:159], v[206:209], v[48:63]
	v_mfma_f32_32x32x16_bf16 v[64:79], v[156:159], v[148:151], v[64:79]
	s_waitcnt lgkmcnt(0)
	v_mfma_f32_32x32x16_bf16 v[16:31], v[230:233], v[206:209], v[16:31]
	v_mfma_f32_32x32x16_bf16 v[32:47], v[230:233], v[148:151], v[32:47]
	ds_read_b128 v[202:205], v199 offset:4608
	ds_read_b128 v[206:209], v199 offset:4640
	ds_read_b128 v[210:213], v193
	ds_read_b128 v[214:217], v193 offset:32
	ds_read_b128 v[218:221], v199 offset:4672
	ds_read_b128 v[222:225], v199 offset:4704
	ds_read_b128 v[226:229], v193 offset:64
	ds_read_b128 v[230:233], v193 offset:96
	s_waitcnt lgkmcnt(5)
	v_mfma_f32_32x32x16_bf16 v[144:159], v[202:205], v[210:213], v[0:15]
	s_waitcnt lgkmcnt(4)
	v_mfma_f32_32x32x16_bf16 v[144:159], v[206:209], v[214:217], v[144:159]
	s_waitcnt lgkmcnt(1)
	v_mfma_f32_32x32x16_bf16 v[144:159], v[218:221], v[226:229], v[144:159]
	s_waitcnt lgkmcnt(0)
	v_mfma_f32_32x32x16_bf16 v[144:159], v[222:225], v[230:233], v[144:159]
	s_nop 11
	v_exp_f32_e32 v146, v146
	v_exp_f32_e32 v147, v147
	v_exp_f32_e32 v148, v148
	v_exp_f32_e32 v149, v149
	v_exp_f32_e32 v150, v150
	v_exp_f32_e32 v151, v151
	v_exp_f32_e32 v152, v152
	v_exp_f32_e32 v153, v153
	v_exp_f32_e32 v144, v144
	v_exp_f32_e32 v145, v145
	v_exp_f32_e32 v154, v154
	v_exp_f32_e32 v155, v155
	v_exp_f32_e32 v156, v156
	v_exp_f32_e32 v157, v157
	v_exp_f32_e32 v158, v158
	v_exp_f32_e32 v159, v159
	v_pk_add_f32 v[244:245], v[144:145], v[146:147]
	v_pk_add_f32 v[246:247], v[148:149], v[150:151]
	v_pk_add_f32 v[244:245], v[244:245], v[152:153]
	v_pk_add_f32 v[246:247], v[246:247], v[154:155]
	v_pk_add_f32 v[244:245], v[244:245], v[156:157]
	v_pk_add_f32 v[246:247], v[246:247], v[158:159]
	v_pk_add_f32 v[244:245], v[244:245], v[246:247]
	v_add_f32_e32 v244, v244, v245
	v_add_f32_e32 v196, v196, v244
	v_cvt_pk_bf16_f32 v200, v144, v145
	v_cvt_pk_bf16_f32 v201, v146, v147
	v_cvt_pk_bf16_f32 v202, v148, v149
	v_cvt_pk_bf16_f32 v203, v150, v151
	v_cvt_pk_bf16_f32 v204, v152, v153
	v_cvt_pk_bf16_f32 v205, v154, v155
	v_cvt_pk_bf16_f32 v206, v156, v157
	v_cvt_pk_bf16_f32 v207, v158, v159
	ds_read_b128 v[208:211], v199 offset:13824
	ds_read_b128 v[212:215], v199 offset:13856
	ds_read_b128 v[216:219], v193 offset:36864
	ds_read_b128 v[220:223], v193 offset:36896
	ds_read_b128 v[224:227], v199 offset:13888
	ds_read_b128 v[228:231], v199 offset:13920
	ds_read_b128 v[232:235], v193 offset:36928
	ds_read_b128 v[236:239], v193 offset:36960
	s_waitcnt lgkmcnt(5)
	v_mfma_f32_32x32x16_bf16 v[144:159], v[208:211], v[216:219], v[0:15]
	s_waitcnt lgkmcnt(4)
	v_mfma_f32_32x32x16_bf16 v[144:159], v[212:215], v[220:223], v[144:159]
	ds_read_b128 v[208:211], v198 offset:64
	ds_read_b128 v[212:215], v198 offset:96
	ds_read_b128 v[216:219], v198 offset:4672
	ds_read_b128 v[220:223], v198 offset:4704
	s_waitcnt lgkmcnt(5)
	v_mfma_f32_32x32x16_bf16 v[144:159], v[224:227], v[232:235], v[144:159]
	s_waitcnt lgkmcnt(4)
	v_mfma_f32_32x32x16_bf16 v[144:159], v[228:231], v[236:239], v[144:159]
	s_nop 11
	v_exp_f32_e32 v144, v144
	v_exp_f32_e32 v145, v145
	v_exp_f32_e32 v146, v146
	v_exp_f32_e32 v147, v147
	v_exp_f32_e32 v148, v148
	v_exp_f32_e32 v149, v149
	v_exp_f32_e32 v150, v150
	v_exp_f32_e32 v151, v151
	v_exp_f32_e32 v152, v152
	v_exp_f32_e32 v153, v153
	v_exp_f32_e32 v154, v154
	v_exp_f32_e32 v155, v155
	v_exp_f32_e32 v156, v156
	v_exp_f32_e32 v157, v157
	v_exp_f32_e32 v158, v158
	v_exp_f32_e32 v159, v159
	v_pk_add_f32 v[244:245], v[144:145], v[146:147]
	v_pk_add_f32 v[246:247], v[148:149], v[150:151]
	v_pk_add_f32 v[244:245], v[244:245], v[152:153]
	v_pk_add_f32 v[246:247], v[246:247], v[154:155]
	v_pk_add_f32 v[244:245], v[244:245], v[156:157]
	v_pk_add_f32 v[246:247], v[246:247], v[158:159]
	v_pk_add_f32 v[244:245], v[244:245], v[246:247]
	v_add_f32_e32 v244, v244, v245
	v_add_f32_e32 v197, v197, v244
	v_cvt_pk_bf16_f32 v144, v144, v145
	v_cvt_pk_bf16_f32 v145, v146, v147
	v_cvt_pk_bf16_f32 v146, v148, v149
	v_cvt_pk_bf16_f32 v147, v150, v151
	v_cvt_pk_bf16_f32 v148, v152, v153
	v_cvt_pk_bf16_f32 v149, v154, v155
	v_cvt_pk_bf16_f32 v150, v156, v157
	v_cvt_pk_bf16_f32 v151, v158, v159
	ds_read_b128 v[152:155], v198 offset:9280
	ds_read_b128 v[156:159], v198 offset:9312
	ds_read_b128 v[224:227], v198 offset:13888
	ds_read_b128 v[228:231], v198 offset:13920
	s_waitcnt lgkmcnt(7)
	v_mfma_f32_32x32x16_bf16 v[112:127], v[208:211], v[200:203], v[112:127]
	v_mfma_f32_32x32x16_bf16 v[128:143], v[208:211], v[144:147], v[128:143]
	s_waitcnt lgkmcnt(5)
	v_mfma_f32_32x32x16_bf16 v[80:95], v[216:219], v[200:203], v[80:95]
	v_mfma_f32_32x32x16_bf16 v[96:111], v[216:219], v[144:147], v[96:111]
	v_mfma_f32_32x32x16_bf16 v[112:127], v[212:215], v[204:207], v[112:127]
	v_mfma_f32_32x32x16_bf16 v[128:143], v[212:215], v[148:151], v[128:143]
	s_waitcnt lgkmcnt(4)
	v_mfma_f32_32x32x16_bf16 v[80:95], v[220:223], v[204:207], v[80:95]
	v_mfma_f32_32x32x16_bf16 v[96:111], v[220:223], v[148:151], v[96:111]
	s_waitcnt lgkmcnt(3)
	v_mfma_f32_32x32x16_bf16 v[48:63], v[152:155], v[200:203], v[48:63]
	v_mfma_f32_32x32x16_bf16 v[64:79], v[152:155], v[144:147], v[64:79]
	s_waitcnt lgkmcnt(1)
	v_mfma_f32_32x32x16_bf16 v[16:31], v[224:227], v[200:203], v[16:31]
	v_mfma_f32_32x32x16_bf16 v[32:47], v[224:227], v[144:147], v[32:47]
	v_mfma_f32_32x32x16_bf16 v[48:63], v[156:159], v[204:207], v[48:63]
	v_mfma_f32_32x32x16_bf16 v[64:79], v[156:159], v[148:151], v[64:79]
	s_waitcnt lgkmcnt(0)
	v_mfma_f32_32x32x16_bf16 v[16:31], v[228:231], v[204:207], v[16:31]
	v_mfma_f32_32x32x16_bf16 v[32:47], v[228:231], v[148:151], v[32:47]
	s_branch .LBB0_111

.Lab_B0:
	ds_read_b128 v[202:205], v199
	ds_read_b128 v[206:209], v199 offset:32
	ds_read_b128 v[210:213], v193
	ds_read_b128 v[214:217], v193 offset:32
	ds_read_b128 v[218:221], v199 offset:64
	ds_read_b128 v[222:225], v199 offset:96
	ds_read_b128 v[226:229], v193 offset:64
	ds_read_b128 v[230:233], v193 offset:96
	s_waitcnt lgkmcnt(5)
	v_mfma_f32_32x32x16_bf16 v[144:159], v[202:205], v[210:213], v[0:15]
	s_waitcnt lgkmcnt(4)
	v_mfma_f32_32x32x16_bf16 v[144:159], v[206:209], v[214:217], v[144:159]
	s_waitcnt lgkmcnt(1)
	v_mfma_f32_32x32x16_bf16 v[144:159], v[218:221], v[226:229], v[144:159]
	s_waitcnt lgkmcnt(0)
	v_mfma_f32_32x32x16_bf16 v[144:159], v[222:225], v[230:233], v[144:159]
	s_nop 11
	v_exp_f32_e32 v146, v146
	v_exp_f32_e32 v147, v147
	v_exp_f32_e32 v148, v148
	v_exp_f32_e32 v149, v149
	v_exp_f32_e32 v150, v150
	v_exp_f32_e32 v151, v151
	v_exp_f32_e32 v152, v152
	v_exp_f32_e32 v153, v153
	v_exp_f32_e32 v144, v144
	v_exp_f32_e32 v154, v154
	v_exp_f32_e32 v145, v145
	v_exp_f32_e32 v155, v155
	v_exp_f32_e32 v156, v156
	v_exp_f32_e32 v157, v157
	v_exp_f32_e32 v158, v158
	v_exp_f32_e32 v159, v159
	v_pk_add_f32 v[244:245], v[144:145], v[146:147]
	v_pk_add_f32 v[246:247], v[148:149], v[150:151]
	v_pk_add_f32 v[244:245], v[244:245], v[152:153]
	v_pk_add_f32 v[246:247], v[246:247], v[154:155]
	v_pk_add_f32 v[244:245], v[244:245], v[156:157]
	v_pk_add_f32 v[246:247], v[246:247], v[158:159]
	v_pk_add_f32 v[244:245], v[244:245], v[246:247]
	v_add_f32_e32 v244, v244, v245
	v_add_f32_e32 v196, v196, v244
	v_cvt_pk_bf16_f32 v202, v144, v145
	v_cvt_pk_bf16_f32 v203, v146, v147
	v_cvt_pk_bf16_f32 v204, v148, v149
	v_cvt_pk_bf16_f32 v205, v150, v151
	v_cvt_pk_bf16_f32 v206, v152, v153
	v_cvt_pk_bf16_f32 v207, v154, v155
	v_cvt_pk_bf16_f32 v208, v156, v157
	v_cvt_pk_bf16_f32 v209, v158, v159
	ds_read_b128 v[210:213], v199 offset:9216
	ds_read_b128 v[214:217], v199 offset:9248
	ds_read_b128 v[218:221], v193 offset:36864
	ds_read_b128 v[222:225], v193 offset:36896
	ds_read_b128 v[226:229], v199 offset:9280
	ds_read_b128 v[230:233], v199 offset:9312
	ds_read_b128 v[234:237], v193 offset:36928
	ds_read_b128 v[238:241], v193 offset:36960
	s_waitcnt lgkmcnt(5)
	v_mfma_f32_32x32x16_bf16 v[144:159], v[210:213], v[218:221], v[0:15]
	s_waitcnt lgkmcnt(4)
	v_mfma_f32_32x32x16_bf16 v[144:159], v[214:217], v[222:225], v[144:159]
	ds_read_b128 v[210:213], v198
	ds_read_b128 v[214:217], v198 offset:32
	ds_read_b128 v[218:221], v198 offset:4608
	ds_read_b128 v[222:225], v198 offset:4640
	s_waitcnt lgkmcnt(5)
	v_mfma_f32_32x32x16_bf16 v[144:159], v[226:229], v[234:237], v[144:159]
	s_waitcnt lgkmcnt(4)
	v_mfma_f32_32x32x16_bf16 v[144:159], v[230:233], v[238:241], v[144:159]
	s_nop 11
	v_exp_f32_e32 v144, v144
	v_exp_f32_e32 v145, v145
	v_exp_f32_e32 v146, v146
	v_exp_f32_e32 v147, v147
	v_exp_f32_e32 v148, v148
	v_exp_f32_e32 v149, v149
	v_exp_f32_e32 v150, v150
	v_exp_f32_e32 v151, v151
	v_exp_f32_e32 v152, v152
	v_exp_f32_e32 v153, v153
	v_exp_f32_e32 v154, v154
	v_exp_f32_e32 v155, v155
	v_exp_f32_e32 v156, v156
	v_exp_f32_e32 v157, v157
	v_exp_f32_e32 v158, v158
	v_exp_f32_e32 v159, v159
	v_pk_add_f32 v[244:245], v[144:145], v[146:147]
	v_pk_add_f32 v[246:247], v[148:149], v[150:151]
	v_pk_add_f32 v[244:245], v[244:245], v[152:153]
	v_pk_add_f32 v[246:247], v[246:247], v[154:155]
	v_pk_add_f32 v[244:245], v[244:245], v[156:157]
	v_pk_add_f32 v[246:247], v[246:247], v[158:159]
	v_pk_add_f32 v[244:245], v[244:245], v[246:247]
	v_add_f32_e32 v244, v244, v245
	v_add_f32_e32 v197, v197, v244
	v_cvt_pk_bf16_f32 v144, v144, v145
	v_cvt_pk_bf16_f32 v145, v146, v147
	v_cvt_pk_bf16_f32 v146, v148, v149
	v_cvt_pk_bf16_f32 v147, v150, v151
	v_cvt_pk_bf16_f32 v148, v152, v153
	v_cvt_pk_bf16_f32 v149, v154, v155
	v_cvt_pk_bf16_f32 v150, v156, v157
	v_cvt_pk_bf16_f32 v151, v158, v159
	ds_read_b128 v[152:155], v198 offset:9216
	ds_read_b128 v[156:159], v198 offset:9248
	ds_read_b128 v[226:229], v198 offset:13824
	ds_read_b128 v[230:233], v198 offset:13856
	s_waitcnt lgkmcnt(7)
	v_mfma_f32_32x32x16_bf16 v[112:127], v[210:213], v[202:205], v[112:127]
	v_mfma_f32_32x32x16_bf16 v[128:143], v[210:213], v[144:147], v[128:143]
	s_waitcnt lgkmcnt(5)
	v_mfma_f32_32x32x16_bf16 v[80:95], v[218:221], v[202:205], v[80:95]
	v_mfma_f32_32x32x16_bf16 v[96:111], v[218:221], v[144:147], v[96:111]
	v_mfma_f32_32x32x16_bf16 v[112:127], v[214:217], v[206:209], v[112:127]
	v_mfma_f32_32x32x16_bf16 v[128:143], v[214:217], v[148:151], v[128:143]
	s_waitcnt lgkmcnt(4)
	v_mfma_f32_32x32x16_bf16 v[80:95], v[222:225], v[206:209], v[80:95]
	v_mfma_f32_32x32x16_bf16 v[96:111], v[222:225], v[148:151], v[96:111]
	s_waitcnt lgkmcnt(3)
	v_mfma_f32_32x32x16_bf16 v[48:63], v[152:155], v[202:205], v[48:63]
	v_mfma_f32_32x32x16_bf16 v[64:79], v[152:155], v[144:147], v[64:79]
	s_waitcnt lgkmcnt(1)
	v_mfma_f32_32x32x16_bf16 v[16:31], v[226:229], v[202:205], v[16:31]
	v_mfma_f32_32x32x16_bf16 v[32:47], v[226:229], v[144:147], v[32:47]
	v_mfma_f32_32x32x16_bf16 v[48:63], v[156:159], v[206:209], v[48:63]
	v_mfma_f32_32x32x16_bf16 v[64:79], v[156:159], v[148:151], v[64:79]
	s_waitcnt lgkmcnt(0)
	v_mfma_f32_32x32x16_bf16 v[16:31], v[230:233], v[206:209], v[16:31]
	v_mfma_f32_32x32x16_bf16 v[32:47], v[230:233], v[148:151], v[32:47]
	ds_read_b128 v[202:205], v199 offset:4608
	ds_read_b128 v[206:209], v199 offset:4640
	ds_read_b128 v[210:213], v193
	ds_read_b128 v[214:217], v193 offset:32
	ds_read_b128 v[218:221], v199 offset:4672
	ds_read_b128 v[222:225], v199 offset:4704
	ds_read_b128 v[226:229], v193 offset:64
	ds_read_b128 v[230:233], v193 offset:96
	s_waitcnt lgkmcnt(5)
	v_mfma_f32_32x32x16_bf16 v[144:159], v[202:205], v[210:213], v[0:15]
	s_waitcnt lgkmcnt(4)
	v_mfma_f32_32x32x16_bf16 v[144:159], v[206:209], v[214:217], v[144:159]
	s_waitcnt lgkmcnt(1)
	v_mfma_f32_32x32x16_bf16 v[144:159], v[218:221], v[226:229], v[144:159]
	s_waitcnt lgkmcnt(0)
	v_mfma_f32_32x32x16_bf16 v[144:159], v[222:225], v[230:233], v[144:159]
	s_nop 11
	v_exp_f32_e32 v146, v146
	v_exp_f32_e32 v147, v147
	v_exp_f32_e32 v148, v148
	v_exp_f32_e32 v149, v149
	v_exp_f32_e32 v150, v150
	v_exp_f32_e32 v151, v151
	v_exp_f32_e32 v152, v152
	v_exp_f32_e32 v153, v153
	v_exp_f32_e32 v144, v144
	v_exp_f32_e32 v145, v145
	v_exp_f32_e32 v154, v154
	v_exp_f32_e32 v155, v155
	v_exp_f32_e32 v156, v156
	v_exp_f32_e32 v157, v157
	v_exp_f32_e32 v158, v158
	v_exp_f32_e32 v159, v159
	v_pk_add_f32 v[244:245], v[144:145], v[146:147]
	v_pk_add_f32 v[246:247], v[148:149], v[150:151]
	v_pk_add_f32 v[244:245], v[244:245], v[152:153]
	v_pk_add_f32 v[246:247], v[246:247], v[154:155]
	v_pk_add_f32 v[244:245], v[244:245], v[156:157]
	v_pk_add_f32 v[246:247], v[246:247], v[158:159]
	v_pk_add_f32 v[244:245], v[244:245], v[246:247]
	v_add_f32_e32 v244, v244, v245
	v_add_f32_e32 v196, v196, v244
	v_cvt_pk_bf16_f32 v200, v144, v145
	v_cvt_pk_bf16_f32 v201, v146, v147
	v_cvt_pk_bf16_f32 v202, v148, v149
	v_cvt_pk_bf16_f32 v203, v150, v151
	v_cvt_pk_bf16_f32 v204, v152, v153
	v_cvt_pk_bf16_f32 v205, v154, v155
	v_cvt_pk_bf16_f32 v206, v156, v157
	v_cvt_pk_bf16_f32 v207, v158, v159
	ds_read_b128 v[208:211], v199 offset:13824
	ds_read_b128 v[212:215], v199 offset:13856
	ds_read_b128 v[216:219], v193 offset:36864
	ds_read_b128 v[220:223], v193 offset:36896
	ds_read_b128 v[224:227], v199 offset:13888
	ds_read_b128 v[228:231], v199 offset:13920
	ds_read_b128 v[232:235], v193 offset:36928
	ds_read_b128 v[236:239], v193 offset:36960
	s_waitcnt lgkmcnt(5)
	v_mfma_f32_32x32x16_bf16 v[144:159], v[208:211], v[216:219], v[0:15]
	s_waitcnt lgkmcnt(4)
	v_mfma_f32_32x32x16_bf16 v[144:159], v[212:215], v[220:223], v[144:159]
	ds_read_b128 v[208:211], v198 offset:64
	ds_read_b128 v[212:215], v198 offset:96
	ds_read_b128 v[216:219], v198 offset:4672
	ds_read_b128 v[220:223], v198 offset:4704
	s_waitcnt lgkmcnt(5)
	v_mfma_f32_32x32x16_bf16 v[144:159], v[224:227], v[232:235], v[144:159]
	s_waitcnt lgkmcnt(4)
	v_mfma_f32_32x32x16_bf16 v[144:159], v[228:231], v[236:239], v[144:159]
	s_nop 11
	v_exp_f32_e32 v144, v144
	v_exp_f32_e32 v145, v145
	v_exp_f32_e32 v146, v146
	v_exp_f32_e32 v147, v147
	v_exp_f32_e32 v148, v148
	v_exp_f32_e32 v149, v149
	v_exp_f32_e32 v150, v150
	v_exp_f32_e32 v151, v151
	v_exp_f32_e32 v152, v152
	v_exp_f32_e32 v153, v153
	v_exp_f32_e32 v154, v154
	v_exp_f32_e32 v155, v155
	v_exp_f32_e32 v156, v156
	v_exp_f32_e32 v157, v157
	v_exp_f32_e32 v158, v158
	v_exp_f32_e32 v159, v159
	v_pk_add_f32 v[244:245], v[144:145], v[146:147]
	v_pk_add_f32 v[246:247], v[148:149], v[150:151]
	v_pk_add_f32 v[244:245], v[244:245], v[152:153]
	v_pk_add_f32 v[246:247], v[246:247], v[154:155]
	v_pk_add_f32 v[244:245], v[244:245], v[156:157]
	v_pk_add_f32 v[246:247], v[246:247], v[158:159]
	v_pk_add_f32 v[244:245], v[244:245], v[246:247]
	v_add_f32_e32 v244, v244, v245
	v_add_f32_e32 v197, v197, v244
	v_cvt_pk_bf16_f32 v144, v144, v145
	v_cvt_pk_bf16_f32 v145, v146, v147
	v_cvt_pk_bf16_f32 v146, v148, v149
	v_cvt_pk_bf16_f32 v147, v150, v151
	v_cvt_pk_bf16_f32 v148, v152, v153
	v_cvt_pk_bf16_f32 v149, v154, v155
	v_cvt_pk_bf16_f32 v150, v156, v157
	v_cvt_pk_bf16_f32 v151, v158, v159
	ds_read_b128 v[152:155], v198 offset:9280
	ds_read_b128 v[156:159], v198 offset:9312
	ds_read_b128 v[224:227], v198 offset:13888
	ds_read_b128 v[228:231], v198 offset:13920
	s_add_i32 s4, s42, 1
	s_cmp_lt_u32 s4, s98
	s_cbranch_scc1 .LBB0_111
	s_waitcnt lgkmcnt(7)
	v_mfma_f32_32x32x16_bf16 v[112:127], v[208:211], v[200:203], v[112:127]
	v_mfma_f32_32x32x16_bf16 v[128:143], v[208:211], v[144:147], v[128:143]
	s_waitcnt lgkmcnt(5)
	v_mfma_f32_32x32x16_bf16 v[80:95], v[216:219], v[200:203], v[80:95]
	v_mfma_f32_32x32x16_bf16 v[96:111], v[216:219], v[144:147], v[96:111]
	v_mfma_f32_32x32x16_bf16 v[112:127], v[212:215], v[204:207], v[112:127]
	v_mfma_f32_32x32x16_bf16 v[128:143], v[212:215], v[148:151], v[128:143]
	s_waitcnt lgkmcnt(4)
	v_mfma_f32_32x32x16_bf16 v[80:95], v[220:223], v[204:207], v[80:95]
	v_mfma_f32_32x32x16_bf16 v[96:111], v[220:223], v[148:151], v[96:111]
	s_waitcnt lgkmcnt(3)
	v_mfma_f32_32x32x16_bf16 v[48:63], v[152:155], v[200:203], v[48:63]
	v_mfma_f32_32x32x16_bf16 v[64:79], v[152:155], v[144:147], v[64:79]
	s_waitcnt lgkmcnt(1)
	v_mfma_f32_32x32x16_bf16 v[16:31], v[224:227], v[200:203], v[16:31]
	v_mfma_f32_32x32x16_bf16 v[32:47], v[224:227], v[144:147], v[32:47]
	v_mfma_f32_32x32x16_bf16 v[48:63], v[156:159], v[204:207], v[48:63]
	v_mfma_f32_32x32x16_bf16 v[64:79], v[156:159], v[148:151], v[64:79]
	s_waitcnt lgkmcnt(0)
	v_mfma_f32_32x32x16_bf16 v[16:31], v[228:231], v[204:207], v[16:31]
	v_mfma_f32_32x32x16_bf16 v[32:47], v[228:231], v[148:151], v[32:47]
	s_branch .LBB0_111
